# plus XCD-aware PEER query GEMM item order (all heads of an m-tile on one XCD)
# speedup vs baseline: 1.0239x; 1.0043x over previous
; DI void peer1_phase(const Params& p, unsigned char* smem, const bf16* __restrict__ A, const bf16* __restrict__ Bt, int layer) {
;     ...
;   for (int item = blockIdx.x; item < 1024; item += gridDim.x) {
;     const int mt = item >> 3, hh = item & 7;
;     const int m0 = mt * 128;
;     for (int half = 0; half < 2; ++half) {
;       const int n0 = (2 * hh + half) * 128;
.LBB0_610:
	s_mov_b32 s98, s83
	s_cmp_lg_u32 s26, 0x200
	s_cbranch_scc1 .Lmy_ir_p1L0
	s_and_b32 s98, s83, 7
	s_bfe_u32 s99, s83, 0x60003
	s_lshr_b32 s100, s83, 9
	s_lshl_b32 s100, s100, 6
	s_add_i32 s99, s99, s100
	s_lshr_b32 s100, s99, 3
	s_lshl_b32 s100, s100, 3
	s_add_i32 s98, s98, s100
	s_and_b32 s99, s99, 7
	s_lshl_b32 s98, s98, 3
	s_or_b32 s98, s98, s99
.Lmy_ir_p1L0:
	s_and_b32 s18, s98, 7
	s_lshl_b32 s0, s98, 4
	s_and_b32 s84, s0, 0xffffff80
	s_ashr_i32 s5, s98, 3
	s_lshl_b32 s0, s18, 14
	s_lshl_b32 s4, s18, 8
	s_mul_i32 s5, s5, 5
	s_mov_b32 s85, 0
	s_mov_b64 s[28:29], -1
	s_lshl_b32 s30, s0, 1
	s_branch .LBB0_612

; DI void peer1_phase(const Params& p, unsigned char* smem, const bf16* __restrict__ A, const bf16* __restrict__ Bt, int layer) {
;     ...
;   for (int item = blockIdx.x; item < 1024; item += gridDim.x) {
;     const int mt = item >> 3, hh = item & 7;
;     const int m0 = mt * 128;
;     for (int half = 0; half < 2; ++half) {
;       const int n0 = (2 * hh + half) * 128;
.Lmy_ir_p1L1:
	s_and_b32 s16, s98, 7
	s_lshl_b32 s0, s98, 4
	s_and_b32 s84, s0, 0xffffff80
	s_lshl_b32 s0, s16, 14
	s_ashr_i32 s5, s98, 3
	s_bitset1_b32 s0, 18
	s_lshl_b32 s4, s16, 8
	s_mul_i32 s5, s5, 5
	s_lshl_b32 s30, s0, 1
	s_mov_b64 s[28:29], -1
	s_mov_b32 s85, 0
	s_branch .LBB0_1435
